# P5: lean epilogue (batched part2 loads) + column-tile rotation per XCD so in-flight tiles cover all 16 column blocks
# speedup vs baseline: 1.0154x; 1.0154x over previous
.LBB0_759:
	s_cmp_lt_i32 s86, 6
	s_cselect_b64 s[0:1], -1, 0
	s_and_b64 s[4:5], s[0:1], s[2:3]
	s_andn2_b64 vcc, exec, s[4:5]
	s_cbranch_vccnz .LBB0_776
	s_cmpk_gt_i32 s76, 0x17ff
	v_readfirstlane_b32 s2, v161
	s_cbranch_scc1 .LBB0_776
	v_lshrrev_b32_e32 v0, 5, v161
	v_lshrrev_b32_e32 v2, 1, v161
	v_and_b32_e32 v0, 4, v0
	s_waitcnt lgkmcnt(0)
	v_bfe_u32 v1, v161, 2, 2
	v_and_b32_e32 v11, 24, v2
	v_or3_b32 v0, v0, v1, v11
	v_lshlrev_b32_e32 v1, 4, v161
	v_add_u32_e32 v8, 0x2000, v1
	v_lshrrev_b32_e32 v2, 7, v8
	s_movk_i32 s1, 0xe0
	v_and_b32_e32 v4, 32, v161
	v_and_or_b32 v3, v2, s1, v0
	v_bitop3_b32 v9, v1, v4, 48 bitop3:0x6c
	v_and_b32_e32 v10, 64, v161
	v_bfe_u32 v12, v161, 2, 4
	s_movk_i32 s1, 0xf0
	v_or_b32_e32 v1, v9, v10
	v_and_or_b32 v2, v2, s1, v12
	v_lshl_or_b32 v130, v2, 11, v1
	v_lshrrev_b32_e32 v2, 3, v161
	s_movk_i32 s1, 0x60
	v_and_or_b32 v0, v2, s1, v0
	s_movk_i32 s1, 0x70
	v_lshl_or_b32 v132, v0, 11, v1
	v_and_or_b32 v0, v2, s1, v12
	s_ashr_i32 s1, s76, 31
	s_lshr_b32 s10, s1, 29
	s_add_i32 s10, s76, s10
	s_lshr_b32 s12, s2, 6
	s_ashr_i32 s11, s10, 3
	s_and_b32 s10, s10, -8
	s_lshr_b32 s3, s2, 8
	s_lshl_b32 s0, s12, 10
	s_sub_i32 s10, s76, s10
	s_cmp_lt_i32 s10, 0
	s_movk_i32 s14, 0x301
	s_cselect_b32 s13, s14, 0x300
	s_mul_i32 s10, s10, s13
	s_add_i32 s10, s10, s11
	s_ashr_i32 s11, s10, 31
	s_lshr_b32 s11, s11, 25
	s_add_i32 s11, s10, s11
	s_ashr_i32 s13, s11, 7
	s_and_b32 s11, s11, 0xffffff80
	s_sub_i32 s10, s10, s11
	s_bfe_i32 s11, s10, 0x80000
	s_bfe_u32 s11, s11, 0x3000c
	s_add_i32 s11, s10, s11
	s_bfe_i32 s15, s11, 0x80000
	s_and_b32 s11, s11, 0xf8
	s_sub_i32 s10, s10, s11
	s_lshl_b32 s13, s13, 3
	s_sext_i32_i16 s15, s15
	s_sext_i32_i8 s10, s10
	s_add_i32 s26, s13, s10
	s_ashr_i32 s34, s15, 3
	s_and_b32 s98, s76, 3
	s_lshl2_add_u32 s34, s98, s34
	s_and_b32 s34, s34, 15
	s_ashr_i32 s16, s15, 8
	s_ashr_i32 s27, s26, 31
	s_lshl_b32 s13, s34, 19
	s_ashr_i32 s17, s16, 31
	s_lshl_b64 s[10:11], s[26:27], 19
	s_and_b32 s13, s13, 0xf80000
	s_lshl_b64 s[16:17], s[16:17], 24
	s_add_u32 s15, s60, s16
	s_addc_u32 s16, s61, s17
	s_add_u32 s30, s15, s13
	s_addc_u32 s31, s16, 0
	s_add_i32 s15, s0, 0
	s_add_i32 m0, s15, 0x10000
	v_lshl_or_b32 v128, v3, 11, v1
	global_load_lds_dwordx4 v132, s[30:31]
	s_add_i32 m0, s15, 0x12000
	s_add_u32 s16, s30, 0x40000
	global_load_lds_dwordx4 v128, s[30:31]
	s_addc_u32 s17, s31, 0
	s_add_i32 m0, s15, 0x14000
	v_lshl_or_b32 v134, v0, 11, v1
	global_load_lds_dwordx4 v132, s[16:17]
	s_add_i32 m0, s15, 0x16000
	s_add_u32 s28, s20, s10
	s_addc_u32 s29, s21, s11
	s_add_i32 s27, s15, 0x2000
	global_load_lds_dwordx4 v128, s[16:17]
	s_mov_b32 m0, s15
	s_add_u32 s10, s28, 0x40000
	global_load_lds_dwordx4 v134, s[28:29]
	s_mov_b32 m0, s27
	s_addc_u32 s11, s29, 0
	s_add_i32 s33, s15, 0x4000
	global_load_lds_dwordx4 v130, s[28:29]
	s_mov_b32 m0, s33
	s_add_i32 s35, s15, 0x6000
	global_load_lds_dwordx4 v134, s[10:11]
	s_mov_b32 m0, s35
	v_mov_b32_e32 v133, 0
	global_load_lds_dwordx4 v130, s[10:11]
	v_mov_b32_e32 v129, v133
	v_mov_b32_e32 v135, v133
	v_mov_b32_e32 v131, v133
	s_cmp_eq_u32 s3, 1
	s_mov_b32 s38, 0
	v_lshl_add_u64 v[6:7], s[30:31], 0, v[132:133]
	v_lshl_add_u64 v[4:5], s[30:31], 0, v[128:129]
	v_lshl_add_u64 v[0:1], s[28:29], 0, v[134:135]
	s_cselect_b64 s[10:11], -1, 0
	s_cmp_lg_u32 s3, 1
	v_lshl_add_u64 v[2:3], s[28:29], 0, v[130:131]
	s_cbranch_scc1 .LBB0_763
	s_barrier

.LBB0_766:
	s_add_i32 s38, s38, 1
	s_mul_i32 s2, s38, s41
	s_mul_hi_u32 s3, s38, s85
	s_add_i32 s3, s3, s2
	s_mul_i32 s2, s38, s85
	s_add_u32 s22, s2, s76
	s_addc_u32 s23, s3, s1
	v_cmp_gt_i64_e32 vcc, s[22:23], v[142:143]
	v_cmp_lt_i64_e64 s[2:3], s[22:23], v[140:141]
	s_cbranch_vccnz .LBB0_768
	s_ashr_i32 s18, s22, 31
	s_lshr_b32 s18, s18, 29
	s_add_i32 s18, s22, s18
	s_ashr_i32 s19, s18, 3
	s_and_b32 s18, s18, -8
	s_sub_i32 s18, s22, s18
	s_cmp_lt_i32 s18, 0
	s_cselect_b32 s22, s14, 0x300
	s_mul_i32 s18, s18, s22
	s_add_i32 s18, s18, s19
	s_ashr_i32 s19, s18, 31
	s_lshr_b32 s19, s19, 25
	s_add_i32 s19, s18, s19
	s_ashr_i32 s22, s19, 7
	s_lshl_b32 s22, s22, 3
	s_sub_i32 s23, 0x180, s22
	s_min_i32 s23, s23, 8
	s_abs_i32 s24, s23
	v_cvt_f32_u32_e32 v0, s24
	s_sub_i32 s36, 0, s24
	s_and_b32 s19, s19, 0xffffff80
	s_sub_i32 s18, s18, s19
	v_rcp_iflag_f32_e32 v0, v0
	s_abs_i32 s19, s18
	s_xor_b32 s25, s18, s23
	s_ashr_i32 s25, s25, 31
	v_mul_f32_e32 v0, 0x4f7ffffe, v0
	v_cvt_u32_f32_e32 v0, v0
	s_nop 0
	v_readfirstlane_b32 s37, v0
	s_mul_i32 s36, s36, s37
	s_mul_hi_u32 s36, s37, s36
	s_add_i32 s37, s37, s36
	s_mul_hi_u32 s36, s19, s37
	s_mul_i32 s37, s36, s24
	s_sub_i32 s19, s19, s37
	s_add_i32 s48, s36, 1
	s_sub_i32 s37, s19, s24
	s_cmp_ge_u32 s19, s24
	s_cselect_b32 s36, s48, s36
	s_cselect_b32 s19, s37, s19
	s_add_i32 s37, s36, 1
	s_cmp_ge_u32 s19, s24
	s_cselect_b32 s19, s37, s36
	s_xor_b32 s19, s19, s25
	s_sub_i32 s48, s19, s25
	s_mul_i32 s19, s48, s23
	s_sub_i32 s18, s18, s19
	s_add_i32 s18, s22, s18
	s_and_b32 s98, s76, 3
	s_lshl2_add_u32 s48, s98, s48
	s_and_b32 s48, s48, 15

.LBB0_772:
	v_lshl_add_u32 v144, s26, 8, v146
	v_and_b32_e32 v153, 24, v148
	v_lshl_or_b32 v158, s34, 8, v148
	v_lshlrev_b32_e32 v153, 1, v153
	v_lshlrev_b32_e32 v158, 1, v158
	v_lshl_add_u32 v153, v144, 6, v153
	v_lshl_add_u32 v158, v144, 13, v158
	v_add_u32_e32 v145, 0x2000, v153
	global_load_dwordx4 v[162:165], v153, s[8:9]
	global_load_dwordx4 v[166:169], v153, s[8:9] offset:1024
	global_load_dwordx4 v[170:173], v153, s[8:9] offset:2048
	global_load_dwordx4 v[174:177], v153, s[8:9] offset:3072
	global_load_dwordx4 v[178:181], v145, s[8:9]
	global_load_dwordx4 v[182:185], v145, s[8:9] offset:1024
	global_load_dwordx4 v[186:189], v145, s[8:9] offset:2048
	global_load_dwordx4 v[190:193], v145, s[8:9] offset:3072
	v_max_f32_e32 v127, 0, v127
	v_max_f32_e32 v126, 0, v126
	v_max_f32_e32 v125, 0, v125
	v_max_f32_e32 v124, 0, v124
	v_max_f32_e32 v123, 0, v123
	v_max_f32_e32 v122, 0, v122
	v_max_f32_e32 v121, 0, v121
	v_max_f32_e32 v120, 0, v120
	v_max_f32_e32 v119, 0, v119
	v_max_f32_e32 v118, 0, v118
	v_max_f32_e32 v117, 0, v117
	v_max_f32_e32 v116, 0, v116
	v_max_f32_e32 v115, 0, v115
	v_max_f32_e32 v114, 0, v114
	v_max_f32_e32 v113, 0, v113
	v_max_f32_e32 v112, 0, v112
	v_max_f32_e32 v111, 0, v111
	v_max_f32_e32 v110, 0, v110
	v_max_f32_e32 v109, 0, v109
	v_max_f32_e32 v108, 0, v108
	v_max_f32_e32 v107, 0, v107
	v_max_f32_e32 v106, 0, v106
	v_max_f32_e32 v105, 0, v105
	v_max_f32_e32 v104, 0, v104
	v_max_f32_e32 v103, 0, v103
	v_max_f32_e32 v102, 0, v102
	v_max_f32_e32 v101, 0, v101
	v_max_f32_e32 v100, 0, v100
	v_max_f32_e32 v99, 0, v99
	v_max_f32_e32 v98, 0, v98
	v_max_f32_e32 v97, 0, v97
	v_max_f32_e32 v96, 0, v96
	v_max_f32_e32 v95, 0, v95
	v_max_f32_e32 v94, 0, v94
	v_max_f32_e32 v93, 0, v93
	v_max_f32_e32 v92, 0, v92
	v_max_f32_e32 v91, 0, v91
	v_max_f32_e32 v90, 0, v90
	v_max_f32_e32 v89, 0, v89
	v_max_f32_e32 v88, 0, v88
	v_max_f32_e32 v87, 0, v87
	v_max_f32_e32 v86, 0, v86
	v_max_f32_e32 v85, 0, v85
	v_max_f32_e32 v84, 0, v84
	v_max_f32_e32 v83, 0, v83
	v_max_f32_e32 v82, 0, v82
	v_max_f32_e32 v81, 0, v81
	v_max_f32_e32 v80, 0, v80
	v_max_f32_e32 v79, 0, v79
	v_max_f32_e32 v78, 0, v78
	v_max_f32_e32 v77, 0, v77
	v_max_f32_e32 v76, 0, v76
	v_max_f32_e32 v75, 0, v75
	v_max_f32_e32 v74, 0, v74
	v_max_f32_e32 v73, 0, v73
	v_max_f32_e32 v72, 0, v72
	v_max_f32_e32 v71, 0, v71
	v_max_f32_e32 v70, 0, v70
	v_max_f32_e32 v69, 0, v69
	v_max_f32_e32 v68, 0, v68
	v_max_f32_e32 v67, 0, v67
	v_max_f32_e32 v66, 0, v66
	v_max_f32_e32 v65, 0, v65
	v_max_f32_e32 v64, 0, v64
	v_max_f32_e32 v63, 0, v63
	v_max_f32_e32 v62, 0, v62
	v_max_f32_e32 v61, 0, v61
	v_max_f32_e32 v60, 0, v60
	v_max_f32_e32 v59, 0, v59
	v_max_f32_e32 v58, 0, v58
	v_max_f32_e32 v57, 0, v57
	v_max_f32_e32 v56, 0, v56
	v_max_f32_e32 v55, 0, v55
	v_max_f32_e32 v54, 0, v54
	v_max_f32_e32 v53, 0, v53
	v_max_f32_e32 v52, 0, v52
	v_max_f32_e32 v51, 0, v51
	v_max_f32_e32 v50, 0, v50
	v_max_f32_e32 v49, 0, v49
	v_max_f32_e32 v48, 0, v48
	v_max_f32_e32 v47, 0, v47
	v_max_f32_e32 v46, 0, v46
	v_max_f32_e32 v45, 0, v45
	v_max_f32_e32 v44, 0, v44
	v_max_f32_e32 v43, 0, v43
	v_max_f32_e32 v42, 0, v42
	v_max_f32_e32 v41, 0, v41
	v_max_f32_e32 v40, 0, v40
	v_max_f32_e32 v39, 0, v39
	v_max_f32_e32 v38, 0, v38
	v_max_f32_e32 v37, 0, v37
	v_max_f32_e32 v36, 0, v36
	v_max_f32_e32 v35, 0, v35
	v_max_f32_e32 v34, 0, v34
	v_max_f32_e32 v33, 0, v33
	v_max_f32_e32 v32, 0, v32
	v_max_f32_e32 v31, 0, v31
	v_max_f32_e32 v30, 0, v30
	v_max_f32_e32 v29, 0, v29
	v_max_f32_e32 v28, 0, v28
	v_max_f32_e32 v27, 0, v27
	v_max_f32_e32 v26, 0, v26
	v_max_f32_e32 v25, 0, v25
	v_max_f32_e32 v24, 0, v24
	v_max_f32_e32 v23, 0, v23
	v_max_f32_e32 v22, 0, v22
	v_max_f32_e32 v21, 0, v21
	v_max_f32_e32 v20, 0, v20
	v_max_f32_e32 v19, 0, v19
	v_max_f32_e32 v18, 0, v18
	v_max_f32_e32 v17, 0, v17
	v_max_f32_e32 v16, 0, v16
	v_max_f32_e32 v15, 0, v15
	v_max_f32_e32 v14, 0, v14
	v_max_f32_e32 v13, 0, v13
	v_max_f32_e32 v12, 0, v12
	v_max_f32_e32 v11, 0, v11
	v_max_f32_e32 v10, 0, v10
	v_max_f32_e32 v9, 0, v9
	v_max_f32_e32 v8, 0, v8
	v_max_f32_e32 v7, 0, v7
	v_max_f32_e32 v6, 0, v6
	v_max_f32_e32 v5, 0, v5
	v_max_f32_e32 v4, 0, v4
	v_max_f32_e32 v3, 0, v3
	v_max_f32_e32 v2, 0, v2
	v_max_f32_e32 v1, 0, v1
	v_max_f32_e32 v0, 0, v0
	v_pk_mul_f32 v[126:127], v[126:127], v[126:127]
	v_pk_mul_f32 v[124:125], v[124:125], v[124:125]
	v_pk_mul_f32 v[122:123], v[122:123], v[122:123]
	v_pk_mul_f32 v[120:121], v[120:121], v[120:121]
	v_pk_mul_f32 v[118:119], v[118:119], v[118:119]
	v_pk_mul_f32 v[116:117], v[116:117], v[116:117]
	v_pk_mul_f32 v[114:115], v[114:115], v[114:115]
	v_pk_mul_f32 v[112:113], v[112:113], v[112:113]
	v_pk_mul_f32 v[110:111], v[110:111], v[110:111]
	v_pk_mul_f32 v[108:109], v[108:109], v[108:109]
	v_pk_mul_f32 v[106:107], v[106:107], v[106:107]
	v_pk_mul_f32 v[104:105], v[104:105], v[104:105]
	v_pk_mul_f32 v[102:103], v[102:103], v[102:103]
	v_pk_mul_f32 v[100:101], v[100:101], v[100:101]
	v_pk_mul_f32 v[98:99], v[98:99], v[98:99]
	v_pk_mul_f32 v[96:97], v[96:97], v[96:97]
	v_pk_mul_f32 v[94:95], v[94:95], v[94:95]
	v_pk_mul_f32 v[92:93], v[92:93], v[92:93]
	v_pk_mul_f32 v[90:91], v[90:91], v[90:91]
	v_pk_mul_f32 v[88:89], v[88:89], v[88:89]
	v_pk_mul_f32 v[86:87], v[86:87], v[86:87]
	v_pk_mul_f32 v[84:85], v[84:85], v[84:85]
	v_pk_mul_f32 v[82:83], v[82:83], v[82:83]
	v_pk_mul_f32 v[80:81], v[80:81], v[80:81]
	v_pk_mul_f32 v[78:79], v[78:79], v[78:79]
	v_pk_mul_f32 v[76:77], v[76:77], v[76:77]
	v_pk_mul_f32 v[74:75], v[74:75], v[74:75]
	v_pk_mul_f32 v[72:73], v[72:73], v[72:73]
	v_pk_mul_f32 v[70:71], v[70:71], v[70:71]
	v_pk_mul_f32 v[68:69], v[68:69], v[68:69]
	v_pk_mul_f32 v[66:67], v[66:67], v[66:67]
	v_pk_mul_f32 v[64:65], v[64:65], v[64:65]
	v_pk_mul_f32 v[62:63], v[62:63], v[62:63]
	v_pk_mul_f32 v[60:61], v[60:61], v[60:61]
	v_pk_mul_f32 v[58:59], v[58:59], v[58:59]
	v_pk_mul_f32 v[56:57], v[56:57], v[56:57]
	v_pk_mul_f32 v[54:55], v[54:55], v[54:55]
	v_pk_mul_f32 v[52:53], v[52:53], v[52:53]
	v_pk_mul_f32 v[50:51], v[50:51], v[50:51]
	v_pk_mul_f32 v[48:49], v[48:49], v[48:49]
	v_pk_mul_f32 v[46:47], v[46:47], v[46:47]
	v_pk_mul_f32 v[44:45], v[44:45], v[44:45]
	v_pk_mul_f32 v[42:43], v[42:43], v[42:43]
	v_pk_mul_f32 v[40:41], v[40:41], v[40:41]
	v_pk_mul_f32 v[38:39], v[38:39], v[38:39]
	v_pk_mul_f32 v[36:37], v[36:37], v[36:37]
	v_pk_mul_f32 v[34:35], v[34:35], v[34:35]
	v_pk_mul_f32 v[32:33], v[32:33], v[32:33]
	v_pk_mul_f32 v[30:31], v[30:31], v[30:31]
	v_pk_mul_f32 v[28:29], v[28:29], v[28:29]
	v_pk_mul_f32 v[26:27], v[26:27], v[26:27]
	v_pk_mul_f32 v[24:25], v[24:25], v[24:25]
	v_pk_mul_f32 v[22:23], v[22:23], v[22:23]
	v_pk_mul_f32 v[20:21], v[20:21], v[20:21]
	v_pk_mul_f32 v[18:19], v[18:19], v[18:19]
	v_pk_mul_f32 v[16:17], v[16:17], v[16:17]
	v_pk_mul_f32 v[14:15], v[14:15], v[14:15]
	v_pk_mul_f32 v[12:13], v[12:13], v[12:13]
	v_pk_mul_f32 v[10:11], v[10:11], v[10:11]
	v_pk_mul_f32 v[8:9], v[8:9], v[8:9]
	v_pk_mul_f32 v[6:7], v[6:7], v[6:7]
	v_pk_mul_f32 v[4:5], v[4:5], v[4:5]
	v_pk_mul_f32 v[2:3], v[2:3], v[2:3]
	v_pk_mul_f32 v[0:1], v[0:1], v[0:1]
	s_waitcnt vmcnt(0)
	v_add_f32_e32 v194, v162, v163
	v_add_f32_e32 v195, v166, v167
	v_add_f32_e32 v196, v170, v171
	v_add_f32_e32 v197, v174, v175
	v_add_f32_e32 v198, v178, v179
	v_add_f32_e32 v199, v182, v183
	v_add_f32_e32 v200, v186, v187
	v_add_f32_e32 v201, v190, v191
	v_add_f32_e32 v202, v164, v165
	v_add_f32_e32 v203, v168, v169
	v_add_f32_e32 v204, v172, v173
	v_add_f32_e32 v205, v176, v177
	v_add_f32_e32 v206, v180, v181
	v_add_f32_e32 v207, v184, v185
	v_add_f32_e32 v208, v188, v189
	v_add_f32_e32 v209, v192, v193
	v_add_f32_e32 v194, v194, v202
	v_add_f32_e32 v195, v195, v203
	v_add_f32_e32 v196, v196, v204
	v_add_f32_e32 v197, v197, v205
	v_add_f32_e32 v198, v198, v206
	v_add_f32_e32 v199, v199, v207
	v_add_f32_e32 v200, v200, v208
	v_add_f32_e32 v201, v201, v209
	v_mov_b32_e32 v202, v194
	v_mov_b32_e32 v203, v195
	v_mov_b32_e32 v204, v196
	v_mov_b32_e32 v205, v197
	v_mov_b32_e32 v206, v198
	v_mov_b32_e32 v207, v199
	v_mov_b32_e32 v208, v200
	v_mov_b32_e32 v209, v201
	v_permlane16_swap_b32_e32 v194, v202
	v_permlane16_swap_b32_e32 v195, v203
	v_permlane16_swap_b32_e32 v196, v204
	v_permlane16_swap_b32_e32 v197, v205
	v_permlane16_swap_b32_e32 v198, v206
	v_permlane16_swap_b32_e32 v199, v207
	v_permlane16_swap_b32_e32 v200, v208
	v_permlane16_swap_b32_e32 v201, v209
	v_add_f32_e32 v194, v194, v202
	v_add_f32_e32 v195, v195, v203
	v_add_f32_e32 v196, v196, v204
	v_add_f32_e32 v197, v197, v205
	v_add_f32_e32 v198, v198, v206
	v_add_f32_e32 v199, v199, v207
	v_add_f32_e32 v200, v200, v208
	v_add_f32_e32 v201, v201, v209
	v_mov_b32_e32 v202, v194
	v_mov_b32_e32 v203, v195
	v_mov_b32_e32 v204, v196
	v_mov_b32_e32 v205, v197
	v_mov_b32_e32 v206, v198
	v_mov_b32_e32 v207, v199
	v_mov_b32_e32 v208, v200
	v_mov_b32_e32 v209, v201
	v_permlane32_swap_b32_e32 v194, v202
	v_permlane32_swap_b32_e32 v195, v203
	v_permlane32_swap_b32_e32 v196, v204
	v_permlane32_swap_b32_e32 v197, v205
	v_permlane32_swap_b32_e32 v198, v206
	v_permlane32_swap_b32_e32 v199, v207
	v_permlane32_swap_b32_e32 v200, v208
	v_permlane32_swap_b32_e32 v201, v209
	v_add_f32_e32 v194, v194, v202
	v_add_f32_e32 v195, v195, v203
	v_add_f32_e32 v196, v196, v204
	v_add_f32_e32 v197, v197, v205
	v_add_f32_e32 v198, v198, v206
	v_add_f32_e32 v199, v199, v207
	v_add_f32_e32 v200, v200, v208
	v_add_f32_e32 v201, v201, v209
	v_fmamk_f32 v194, v194, 0x3a800000, v152
	v_fmamk_f32 v195, v195, 0x3a800000, v152
	v_fmamk_f32 v196, v196, 0x3a800000, v152
	v_fmamk_f32 v197, v197, 0x3a800000, v152
	v_fmamk_f32 v198, v198, 0x3a800000, v152
	v_fmamk_f32 v199, v199, 0x3a800000, v152
	v_fmamk_f32 v200, v200, 0x3a800000, v152
	v_fmamk_f32 v201, v201, 0x3a800000, v152
	v_rcp_f32_e32 v210, v194
	v_rcp_f32_e32 v211, v195
	v_rcp_f32_e32 v212, v196
	v_rcp_f32_e32 v213, v197
	v_rcp_f32_e32 v214, v198
	v_rcp_f32_e32 v215, v199
	v_rcp_f32_e32 v216, v200
	v_rcp_f32_e32 v217, v201
	v_fma_f32 v218, -v194, v210, 1.0
	v_fma_f32 v219, -v195, v211, 1.0
	v_fma_f32 v220, -v196, v212, 1.0
	v_fma_f32 v221, -v197, v213, 1.0
	v_fma_f32 v222, -v198, v214, 1.0
	v_fma_f32 v223, -v199, v215, 1.0
	v_fma_f32 v224, -v200, v216, 1.0
	v_fma_f32 v225, -v201, v217, 1.0
	v_fmac_f32_e32 v210, v218, v210
	v_fmac_f32_e32 v211, v219, v211
	v_fmac_f32_e32 v212, v220, v212
	v_fmac_f32_e32 v213, v221, v213
	v_fmac_f32_e32 v214, v222, v214
	v_fmac_f32_e32 v215, v223, v215
	v_fmac_f32_e32 v216, v224, v216
	v_fmac_f32_e32 v217, v225, v217
	v_fma_f32 v226, -v194, v210, 1.0
	v_fma_f32 v227, -v195, v211, 1.0
	v_fma_f32 v228, -v196, v212, 1.0
	v_fma_f32 v229, -v197, v213, 1.0
	v_fma_f32 v230, -v198, v214, 1.0
	v_fma_f32 v231, -v199, v215, 1.0
	v_fma_f32 v232, -v200, v216, 1.0
	v_fma_f32 v233, -v201, v217, 1.0
	v_fma_f32 v218, v226, v210, v210
	v_fma_f32 v219, v227, v211, v211
	v_fma_f32 v220, v228, v212, v212
	v_fma_f32 v221, v229, v213, v213
	v_fma_f32 v222, v230, v214, v214
	v_fma_f32 v223, v231, v215, v215
	v_fma_f32 v224, v232, v216, v216
	v_fma_f32 v225, v233, v217, v217
	v_fma_f32 v202, -v194, v218, 1.0
	v_fma_f32 v203, -v195, v219, 1.0
	v_fma_f32 v204, -v196, v220, 1.0
	v_fma_f32 v205, -v197, v221, 1.0
	v_fma_f32 v206, -v198, v222, 1.0
	v_fma_f32 v207, -v199, v223, 1.0
	v_fma_f32 v208, -v200, v224, 1.0
	v_fma_f32 v209, -v201, v225, 1.0
	v_fma_f32 v162, v202, v210, v218
	v_fma_f32 v164, v203, v211, v219
	v_fma_f32 v166, v204, v212, v220
	v_fma_f32 v168, v205, v213, v221
	v_fma_f32 v170, v206, v214, v222
	v_fma_f32 v172, v207, v215, v223
	v_fma_f32 v174, v208, v216, v224
	v_fma_f32 v176, v209, v217, v225
	v_pk_mul_f32 v[112:113], v[112:113], v[162:163] op_sel_hi:[1,0]
	v_pk_mul_f32 v[114:115], v[114:115], v[162:163] op_sel_hi:[1,0]
	v_pk_mul_f32 v[116:117], v[116:117], v[162:163] op_sel_hi:[1,0]
	v_pk_mul_f32 v[118:119], v[118:119], v[162:163] op_sel_hi:[1,0]
	v_pk_mul_f32 v[120:121], v[120:121], v[162:163] op_sel_hi:[1,0]
	v_pk_mul_f32 v[122:123], v[122:123], v[162:163] op_sel_hi:[1,0]
	v_pk_mul_f32 v[124:125], v[124:125], v[162:163] op_sel_hi:[1,0]
	v_pk_mul_f32 v[126:127], v[126:127], v[162:163] op_sel_hi:[1,0]
	v_cvt_pk_bf16_f32 v124, v124, v125
	v_cvt_pk_bf16_f32 v125, v126, v127
	v_cvt_pk_bf16_f32 v126, v120, v121
	v_cvt_pk_bf16_f32 v127, v122, v123
	v_cvt_pk_bf16_f32 v116, v116, v117
	v_cvt_pk_bf16_f32 v117, v118, v119
	v_cvt_pk_bf16_f32 v118, v112, v113
	v_cvt_pk_bf16_f32 v119, v114, v115
	global_store_dwordx4 v158, v[124:127], s[58:59]
	global_store_dwordx4 v158, v[116:119], s[58:59] offset:256
	v_pk_mul_f32 v[96:97], v[96:97], v[164:165] op_sel_hi:[1,0]
	v_pk_mul_f32 v[98:99], v[98:99], v[164:165] op_sel_hi:[1,0]
	v_pk_mul_f32 v[100:101], v[100:101], v[164:165] op_sel_hi:[1,0]
	v_pk_mul_f32 v[102:103], v[102:103], v[164:165] op_sel_hi:[1,0]
	v_pk_mul_f32 v[104:105], v[104:105], v[164:165] op_sel_hi:[1,0]
	v_pk_mul_f32 v[106:107], v[106:107], v[164:165] op_sel_hi:[1,0]
	v_pk_mul_f32 v[108:109], v[108:109], v[164:165] op_sel_hi:[1,0]
	v_pk_mul_f32 v[110:111], v[110:111], v[164:165] op_sel_hi:[1,0]
	v_add_u32_e32 v159, 0x20000, v158
	v_cvt_pk_bf16_f32 v108, v108, v109
	v_cvt_pk_bf16_f32 v109, v110, v111
	v_cvt_pk_bf16_f32 v110, v104, v105
	v_cvt_pk_bf16_f32 v111, v106, v107
	v_cvt_pk_bf16_f32 v100, v100, v101
	v_cvt_pk_bf16_f32 v101, v102, v103
	v_cvt_pk_bf16_f32 v102, v96, v97
	v_cvt_pk_bf16_f32 v103, v98, v99
	global_store_dwordx4 v159, v[108:111], s[58:59]
	global_store_dwordx4 v159, v[100:103], s[58:59] offset:256
	v_pk_mul_f32 v[80:81], v[80:81], v[166:167] op_sel_hi:[1,0]
	v_pk_mul_f32 v[82:83], v[82:83], v[166:167] op_sel_hi:[1,0]
	v_pk_mul_f32 v[84:85], v[84:85], v[166:167] op_sel_hi:[1,0]
	v_pk_mul_f32 v[86:87], v[86:87], v[166:167] op_sel_hi:[1,0]
	v_pk_mul_f32 v[88:89], v[88:89], v[166:167] op_sel_hi:[1,0]
	v_pk_mul_f32 v[90:91], v[90:91], v[166:167] op_sel_hi:[1,0]
	v_pk_mul_f32 v[92:93], v[92:93], v[166:167] op_sel_hi:[1,0]
	v_pk_mul_f32 v[94:95], v[94:95], v[166:167] op_sel_hi:[1,0]
	v_add_u32_e32 v159, 0x40000, v158
	v_cvt_pk_bf16_f32 v92, v92, v93
	v_cvt_pk_bf16_f32 v93, v94, v95
	v_cvt_pk_bf16_f32 v94, v88, v89
	v_cvt_pk_bf16_f32 v95, v90, v91
	v_cvt_pk_bf16_f32 v84, v84, v85
	v_cvt_pk_bf16_f32 v85, v86, v87
	v_cvt_pk_bf16_f32 v86, v80, v81
	v_cvt_pk_bf16_f32 v87, v82, v83
	global_store_dwordx4 v159, v[92:95], s[58:59]
	global_store_dwordx4 v159, v[84:87], s[58:59] offset:256
	v_pk_mul_f32 v[64:65], v[64:65], v[168:169] op_sel_hi:[1,0]
	v_pk_mul_f32 v[66:67], v[66:67], v[168:169] op_sel_hi:[1,0]
	v_pk_mul_f32 v[68:69], v[68:69], v[168:169] op_sel_hi:[1,0]
	v_pk_mul_f32 v[70:71], v[70:71], v[168:169] op_sel_hi:[1,0]
	v_pk_mul_f32 v[72:73], v[72:73], v[168:169] op_sel_hi:[1,0]
	v_pk_mul_f32 v[74:75], v[74:75], v[168:169] op_sel_hi:[1,0]
	v_pk_mul_f32 v[76:77], v[76:77], v[168:169] op_sel_hi:[1,0]
	v_pk_mul_f32 v[78:79], v[78:79], v[168:169] op_sel_hi:[1,0]
	v_add_u32_e32 v159, 0x60000, v158
	v_cvt_pk_bf16_f32 v76, v76, v77
	v_cvt_pk_bf16_f32 v77, v78, v79
	v_cvt_pk_bf16_f32 v78, v72, v73
	v_cvt_pk_bf16_f32 v79, v74, v75
	v_cvt_pk_bf16_f32 v68, v68, v69
	v_cvt_pk_bf16_f32 v69, v70, v71
	v_cvt_pk_bf16_f32 v70, v64, v65
	v_cvt_pk_bf16_f32 v71, v66, v67
	global_store_dwordx4 v159, v[76:79], s[58:59]
	global_store_dwordx4 v159, v[68:71], s[58:59] offset:256
	v_pk_mul_f32 v[48:49], v[48:49], v[170:171] op_sel_hi:[1,0]
	v_pk_mul_f32 v[50:51], v[50:51], v[170:171] op_sel_hi:[1,0]
	v_pk_mul_f32 v[52:53], v[52:53], v[170:171] op_sel_hi:[1,0]
	v_pk_mul_f32 v[54:55], v[54:55], v[170:171] op_sel_hi:[1,0]
	v_pk_mul_f32 v[56:57], v[56:57], v[170:171] op_sel_hi:[1,0]
	v_pk_mul_f32 v[58:59], v[58:59], v[170:171] op_sel_hi:[1,0]
	v_pk_mul_f32 v[60:61], v[60:61], v[170:171] op_sel_hi:[1,0]
	v_pk_mul_f32 v[62:63], v[62:63], v[170:171] op_sel_hi:[1,0]
	v_add_u32_e32 v159, 0x100000, v158
	v_cvt_pk_bf16_f32 v60, v60, v61
	v_cvt_pk_bf16_f32 v61, v62, v63
	v_cvt_pk_bf16_f32 v62, v56, v57
	v_cvt_pk_bf16_f32 v63, v58, v59
	v_cvt_pk_bf16_f32 v52, v52, v53
	v_cvt_pk_bf16_f32 v53, v54, v55
	v_cvt_pk_bf16_f32 v54, v48, v49
	v_cvt_pk_bf16_f32 v55, v50, v51
	global_store_dwordx4 v159, v[60:63], s[58:59]
	global_store_dwordx4 v159, v[52:55], s[58:59] offset:256
	v_pk_mul_f32 v[32:33], v[32:33], v[172:173] op_sel_hi:[1,0]
	v_pk_mul_f32 v[34:35], v[34:35], v[172:173] op_sel_hi:[1,0]
	v_pk_mul_f32 v[36:37], v[36:37], v[172:173] op_sel_hi:[1,0]
	v_pk_mul_f32 v[38:39], v[38:39], v[172:173] op_sel_hi:[1,0]
	v_pk_mul_f32 v[40:41], v[40:41], v[172:173] op_sel_hi:[1,0]
	v_pk_mul_f32 v[42:43], v[42:43], v[172:173] op_sel_hi:[1,0]
	v_pk_mul_f32 v[44:45], v[44:45], v[172:173] op_sel_hi:[1,0]
	v_pk_mul_f32 v[46:47], v[46:47], v[172:173] op_sel_hi:[1,0]
	v_add_u32_e32 v159, 0x120000, v158
	v_cvt_pk_bf16_f32 v44, v44, v45
	v_cvt_pk_bf16_f32 v45, v46, v47
	v_cvt_pk_bf16_f32 v46, v40, v41
	v_cvt_pk_bf16_f32 v47, v42, v43
	v_cvt_pk_bf16_f32 v36, v36, v37
	v_cvt_pk_bf16_f32 v37, v38, v39
	v_cvt_pk_bf16_f32 v38, v32, v33
	v_cvt_pk_bf16_f32 v39, v34, v35
	global_store_dwordx4 v159, v[44:47], s[58:59]
	global_store_dwordx4 v159, v[36:39], s[58:59] offset:256
	v_pk_mul_f32 v[16:17], v[16:17], v[174:175] op_sel_hi:[1,0]
	v_pk_mul_f32 v[18:19], v[18:19], v[174:175] op_sel_hi:[1,0]
	v_pk_mul_f32 v[20:21], v[20:21], v[174:175] op_sel_hi:[1,0]
	v_pk_mul_f32 v[22:23], v[22:23], v[174:175] op_sel_hi:[1,0]
	v_pk_mul_f32 v[24:25], v[24:25], v[174:175] op_sel_hi:[1,0]
	v_pk_mul_f32 v[26:27], v[26:27], v[174:175] op_sel_hi:[1,0]
	v_pk_mul_f32 v[28:29], v[28:29], v[174:175] op_sel_hi:[1,0]
	v_pk_mul_f32 v[30:31], v[30:31], v[174:175] op_sel_hi:[1,0]
	v_add_u32_e32 v159, 0x140000, v158
	v_cvt_pk_bf16_f32 v28, v28, v29
	v_cvt_pk_bf16_f32 v29, v30, v31
	v_cvt_pk_bf16_f32 v30, v24, v25
	v_cvt_pk_bf16_f32 v31, v26, v27
	v_cvt_pk_bf16_f32 v20, v20, v21
	v_cvt_pk_bf16_f32 v21, v22, v23
	v_cvt_pk_bf16_f32 v22, v16, v17
	v_cvt_pk_bf16_f32 v23, v18, v19
	global_store_dwordx4 v159, v[28:31], s[58:59]
	global_store_dwordx4 v159, v[20:23], s[58:59] offset:256
	v_pk_mul_f32 v[0:1], v[0:1], v[176:177] op_sel_hi:[1,0]
	v_pk_mul_f32 v[2:3], v[2:3], v[176:177] op_sel_hi:[1,0]
	v_pk_mul_f32 v[4:5], v[4:5], v[176:177] op_sel_hi:[1,0]
	v_pk_mul_f32 v[6:7], v[6:7], v[176:177] op_sel_hi:[1,0]
	v_pk_mul_f32 v[8:9], v[8:9], v[176:177] op_sel_hi:[1,0]
	v_pk_mul_f32 v[10:11], v[10:11], v[176:177] op_sel_hi:[1,0]
	v_pk_mul_f32 v[12:13], v[12:13], v[176:177] op_sel_hi:[1,0]
	v_pk_mul_f32 v[14:15], v[14:15], v[176:177] op_sel_hi:[1,0]
	v_add_u32_e32 v159, 0x160000, v158
	v_cvt_pk_bf16_f32 v12, v12, v13
	v_cvt_pk_bf16_f32 v13, v14, v15
	v_cvt_pk_bf16_f32 v14, v8, v9
	v_cvt_pk_bf16_f32 v15, v10, v11
	v_cvt_pk_bf16_f32 v4, v4, v5
	v_cvt_pk_bf16_f32 v5, v6, v7
	v_cvt_pk_bf16_f32 v6, v0, v1
	v_cvt_pk_bf16_f32 v7, v2, v3
	global_store_dwordx4 v159, v[12:15], s[58:59]
	global_store_dwordx4 v159, v[4:7], s[58:59] offset:256
	s_andn2_b64 vcc, exec, s[2:3]
	s_mov_b64 s[2:3], -1
	s_cbranch_vccnz .LBB0_765
	s_andn2_b64 vcc, exec, s[10:11]
	s_cbranch_vccnz .LBB0_764
	s_barrier
	s_branch .LBB0_764

	.amdhsa_kernel _Z9hymba_fwd4Args
		.amdhsa_group_segment_fixed_size 0
		.amdhsa_private_segment_fixed_size 0
		.amdhsa_kernarg_size 376
		.amdhsa_user_sgpr_count 2
		.amdhsa_user_sgpr_dispatch_ptr 0
		.amdhsa_user_sgpr_queue_ptr 0
		.amdhsa_user_sgpr_kernarg_segment_ptr 1
		.amdhsa_user_sgpr_dispatch_id 0
		.amdhsa_user_sgpr_kernarg_preload_length 0
		.amdhsa_user_sgpr_kernarg_preload_offset 0
		.amdhsa_user_sgpr_private_segment_size 0
		.amdhsa_uses_dynamic_stack 0
		.amdhsa_enable_private_segment 0
		.amdhsa_system_sgpr_workgroup_id_x 1
		.amdhsa_system_sgpr_workgroup_id_y 0
		.amdhsa_system_sgpr_workgroup_id_z 0
		.amdhsa_system_sgpr_workgroup_info 0
		.amdhsa_system_vgpr_workitem_id 2
		.amdhsa_next_free_vgpr 249
		.amdhsa_next_free_sgpr 100
		.amdhsa_accum_offset 252
		.amdhsa_reserve_vcc 1
		.amdhsa_float_round_mode_32 0
		.amdhsa_float_round_mode_16_64 0
		.amdhsa_float_denorm_mode_32 3
		.amdhsa_float_denorm_mode_16_64 3
		.amdhsa_dx10_clamp 1
		.amdhsa_ieee_mode 1
		.amdhsa_fp16_overflow 0
		.amdhsa_tg_split 0
		.amdhsa_exception_fp_ieee_invalid_op 0
		.amdhsa_exception_fp_denorm_src 0
		.amdhsa_exception_fp_ieee_div_zero 0
		.amdhsa_exception_fp_ieee_overflow 0
		.amdhsa_exception_fp_ieee_underflow 0
		.amdhsa_exception_fp_ieee_inexact 0
		.amdhsa_exception_int_div_zero 0
	.end_amdhsa_kernel

amdhsa.kernels:
  - .agpr_count:     0
    .args:
      - .offset:         0
        .size:           120
        .value_kind:     by_value
      - .offset:         120
        .size:           4
        .value_kind:     hidden_block_count_x
      - .offset:         124
        .size:           4
        .value_kind:     hidden_block_count_y
      - .offset:         128
        .size:           4
        .value_kind:     hidden_block_count_z
      - .offset:         132
        .size:           2
        .value_kind:     hidden_group_size_x
      - .offset:         134
        .size:           2
        .value_kind:     hidden_group_size_y
      - .offset:         136
        .size:           2
        .value_kind:     hidden_group_size_z
      - .offset:         138
        .size:           2
        .value_kind:     hidden_remainder_x
      - .offset:         140
        .size:           2
        .value_kind:     hidden_remainder_y
      - .offset:         142
        .size:           2
        .value_kind:     hidden_remainder_z
      - .offset:         160
        .size:           8
        .value_kind:     hidden_global_offset_x
      - .offset:         168
        .size:           8
        .value_kind:     hidden_global_offset_y
      - .offset:         176
        .size:           8
        .value_kind:     hidden_global_offset_z
      - .offset:         184
        .size:           2
        .value_kind:     hidden_grid_dims
      - .offset:         208
        .size:           8
        .value_kind:     hidden_multigrid_sync_arg
      - .offset:         240
        .size:           4
        .value_kind:     hidden_dynamic_lds_size
    .group_segment_fixed_size: 0
    .kernarg_segment_align: 8
    .kernarg_segment_size: 376
    .language:       OpenCL C
    .language_version:
      - 2
      - 0
    .max_flat_workgroup_size: 512
    .name:           _Z9hymba_fwd4Args
    .private_segment_fixed_size: 0
    .sgpr_count:     106
    .sgpr_spill_count: 36
    .symbol:         _Z9hymba_fwd4Args.kd
    .uniform_work_group_size: 1
    .uses_dynamic_stack: false
    .vgpr_count:     249
    .vgpr_spill_count: 0
    .wavefront_size: 64
